# P7 weight-copy: FFN2 gate items' gain values loaded in one batch too (stacked on v84)
# speedup vs baseline: 1.0035x; 1.0002x over previous
.LBB0_1598:
	s_andn2_b64 vcc, exec, s[0:1]
	s_cbranch_vccnz .LBB0_1513
	s_mul_hi_i32 s0, s3, 0x2e8ba2e9
	s_lshr_b32 s1, s0, 31
	s_ashr_i32 s4, s0, 3
	s_add_i32 s4, s4, s1
	s_mul_i32 s0, s4, 0xfffff500
	s_add_i32 s10, s12, s0
	s_lshl_b32 s14, s4, 6
	v_or_b32_e32 v86, s14, v66
	s_ashr_i32 s11, s10, 31
	v_lshl_add_u64 v[2:3], s[10:11], 2, v[84:85]
	s_waitcnt vmcnt(0)
	v_or_b32_e32 v6, 4, v86
	v_mad_i64_i32 v[4:5], s[0:1], v86, s28, v[2:3]
	v_mad_i64_i32 v[6:7], s[0:1], v6, s28, v[2:3]
	global_load_dwordx4 v[62:65], v[4:5], off nt
	global_load_dwordx4 v[58:61], v[6:7], off nt
	v_or_b32_e32 v4, 8, v86
	v_or_b32_e32 v6, 12, v86
	v_mad_i64_i32 v[4:5], s[0:1], v4, s28, v[2:3]
	v_mad_i64_i32 v[6:7], s[0:1], v6, s28, v[2:3]
	global_load_dwordx4 v[54:57], v[4:5], off nt
	global_load_dwordx4 v[50:53], v[6:7], off nt
	v_or_b32_e32 v4, 16, v86
	v_or_b32_e32 v6, 20, v86
	v_mad_i64_i32 v[4:5], s[0:1], v4, s28, v[2:3]
	v_mad_i64_i32 v[6:7], s[0:1], v6, s28, v[2:3]
	global_load_dwordx4 v[46:49], v[4:5], off nt
	global_load_dwordx4 v[42:45], v[6:7], off nt
	v_or_b32_e32 v4, 24, v86
	v_or_b32_e32 v6, 28, v86
	v_mad_i64_i32 v[4:5], s[0:1], v4, s28, v[2:3]
	v_mad_i64_i32 v[6:7], s[0:1], v6, s28, v[2:3]
	global_load_dwordx4 v[38:41], v[4:5], off nt
	global_load_dwordx4 v[34:37], v[6:7], off nt
	v_or_b32_e32 v4, 32, v86
	v_or_b32_e32 v6, 36, v86
	v_mad_i64_i32 v[4:5], s[0:1], v4, s28, v[2:3]
	v_mad_i64_i32 v[6:7], s[0:1], v6, s28, v[2:3]
	global_load_dwordx4 v[30:33], v[4:5], off nt
	global_load_dwordx4 v[26:29], v[6:7], off nt
	v_or_b32_e32 v4, 40, v86
	v_or_b32_e32 v6, 44, v86
	v_mad_i64_i32 v[4:5], s[0:1], v4, s28, v[2:3]
	v_mad_i64_i32 v[6:7], s[0:1], v6, s28, v[2:3]
	global_load_dwordx4 v[22:25], v[4:5], off nt
	global_load_dwordx4 v[18:21], v[6:7], off nt
	v_or_b32_e32 v4, 48, v86
	v_or_b32_e32 v6, 52, v86
	v_mad_i64_i32 v[4:5], s[0:1], v4, s28, v[2:3]
	v_mad_i64_i32 v[6:7], s[0:1], v6, s28, v[2:3]
	global_load_dwordx4 v[14:17], v[4:5], off nt
	global_load_dwordx4 v[10:13], v[6:7], off nt
	v_or_b32_e32 v4, 56, v86
	v_or_b32_e32 v6, 60, v86
	v_mad_i64_i32 v[4:5], s[0:1], v4, s28, v[2:3]
	v_mad_i64_i32 v[2:3], s[0:1], v6, s28, v[2:3]
	global_load_dwordx4 v[6:9], v[4:5], off nt
	s_nop 0
	global_load_dwordx4 v[2:5], v[2:3], off nt
	v_cndmask_b32_e64 v68, 0, 1, s[6:7]
	v_cmp_ne_u32_e64 s[0:1], 1, v68
	s_andn2_b64 vcc, exec, s[6:7]
	v_add_u32_e32 v111, v88, v89
	s_cbranch_vccnz .LBB0_1639
	v_readlane_b32 s72, v254, 10
	v_readlane_b32 s82, v254, 20
	v_readlane_b32 s83, v254, 21
	v_ashrrev_i32_e32 v87, 31, v86
	s_mov_b64 s[58:59], s[82:83]
	s_ashr_i32 s15, s14, 31
	v_lshl_add_u64 v[86:87], v[86:87], 2, s[58:59]
	v_lshl_add_u64 v[112:113], s[14:15], 0, v[66:67]
	global_load_dword v86, v[86:87], off
	v_lshl_add_u64 v[112:113], v[112:113], 2, s[58:59]
	global_load_dword v68, v[112:113], off offset:16
	global_load_dword v220, v[112:113], off offset:32
	global_load_dword v221, v[112:113], off offset:48
	global_load_dword v222, v[112:113], off offset:64
	global_load_dword v223, v[112:113], off offset:80
	global_load_dword v224, v[112:113], off offset:96
	global_load_dword v225, v[112:113], off offset:112
	global_load_dword v226, v[112:113], off offset:128
	global_load_dword v227, v[112:113], off offset:144
	global_load_dword v228, v[112:113], off offset:160
	global_load_dword v229, v[112:113], off offset:176
	global_load_dword v230, v[112:113], off offset:192
	global_load_dword v231, v[112:113], off offset:208
	global_load_dword v232, v[112:113], off offset:224
	global_load_dword v233, v[112:113], off offset:240
	v_readlane_b32 s73, v254, 11
	v_readlane_b32 s74, v254, 12
	v_readlane_b32 s75, v254, 13
	v_readlane_b32 s76, v254, 14
	v_readlane_b32 s77, v254, 15
	v_readlane_b32 s78, v254, 16
	v_readlane_b32 s79, v254, 17
	v_readlane_b32 s80, v254, 18
	v_readlane_b32 s81, v254, 19
	v_readlane_b32 s84, v254, 22
	v_readlane_b32 s85, v254, 23
	v_readlane_b32 s86, v254, 24
	v_readlane_b32 s87, v254, 25
	s_waitcnt vmcnt(15)
	v_pk_mul_f32 v[112:113], v[62:63], v[86:87] op_sel_hi:[1,0]
	v_pk_mul_f32 v[86:87], v[64:65], v[86:87] op_sel_hi:[1,0]
	ds_write2_b32 v111, v112, v113 offset1:1
	ds_write2_b32 v111, v86, v87 offset0:2 offset1:3
	s_cbranch_execnz .LBB0_1602

.LBB0_1602:
	s_waitcnt vmcnt(14)
	v_pk_mul_f32 v[58:59], v[58:59], v[68:69] op_sel_hi:[1,0]
	v_add_u32_e32 v62, v88, v99
	ds_write2_b32 v62, v58, v59 offset1:1
	v_pk_mul_f32 v[58:59], v[60:61], v[68:69] op_sel_hi:[1,0]
	ds_write2_b32 v62, v58, v59 offset0:2 offset1:3
	s_and_b64 vcc, exec, s[0:1]
	v_add_u32_e32 v59, v88, v100
	s_cbranch_vccnz .LBB0_1640
	s_ashr_i32 s15, s14, 31
	v_readlane_b32 s72, v254, 10
	v_lshl_add_u64 v[60:61], s[14:15], 0, v[66:67]
	v_readlane_b32 s82, v254, 20
	v_readlane_b32 s83, v254, 21
	v_readlane_b32 s73, v254, 11
	s_nop 0
	v_lshl_add_u64 v[60:61], v[60:61], 2, s[82:83]
	v_readlane_b32 s74, v254, 12
	v_readlane_b32 s75, v254, 13
	v_readlane_b32 s76, v254, 14
	v_readlane_b32 s77, v254, 15
	v_readlane_b32 s78, v254, 16
	v_readlane_b32 s79, v254, 17
	v_readlane_b32 s80, v254, 18
	v_readlane_b32 s81, v254, 19
	v_readlane_b32 s84, v254, 22
	v_readlane_b32 s85, v254, 23
	v_readlane_b32 s86, v254, 24
	v_readlane_b32 s87, v254, 25
	s_waitcnt vmcnt(12)
	v_mov_b32_e32 v62, v220
	v_mov_b32_e32 v58, v221
	v_pk_mul_f32 v[60:61], v[54:55], v[62:63] op_sel_hi:[1,0]
	v_pk_mul_f32 v[62:63], v[56:57], v[62:63] op_sel_hi:[1,0]
	ds_write2_b32 v59, v60, v61 offset1:1
	ds_write2_b32 v59, v62, v63 offset0:2 offset1:3
	s_cbranch_execnz .LBB0_1605

.LBB0_1605:
	s_waitcnt vmcnt(12)
	v_pk_mul_f32 v[50:51], v[50:51], v[58:59] op_sel_hi:[1,0]
	v_add_u32_e32 v54, v88, v101
	ds_write2_b32 v54, v50, v51 offset1:1
	v_pk_mul_f32 v[50:51], v[52:53], v[58:59] op_sel_hi:[1,0]
	ds_write2_b32 v54, v50, v51 offset0:2 offset1:3
	s_and_b64 vcc, exec, s[0:1]
	v_add_u32_e32 v51, v88, v102
	s_cbranch_vccnz .LBB0_1641
	s_ashr_i32 s15, s14, 31
	v_readlane_b32 s72, v254, 10
	v_lshl_add_u64 v[52:53], s[14:15], 0, v[66:67]
	v_readlane_b32 s82, v254, 20
	v_readlane_b32 s83, v254, 21
	v_readlane_b32 s73, v254, 11
	s_nop 0
	v_lshl_add_u64 v[52:53], v[52:53], 2, s[82:83]
	v_readlane_b32 s74, v254, 12
	v_readlane_b32 s75, v254, 13
	v_readlane_b32 s76, v254, 14
	v_readlane_b32 s77, v254, 15
	v_readlane_b32 s78, v254, 16
	v_readlane_b32 s79, v254, 17
	v_readlane_b32 s80, v254, 18
	v_readlane_b32 s81, v254, 19
	v_readlane_b32 s84, v254, 22
	v_readlane_b32 s85, v254, 23
	v_readlane_b32 s86, v254, 24
	v_readlane_b32 s87, v254, 25
	s_waitcnt vmcnt(10)
	v_mov_b32_e32 v54, v222
	v_mov_b32_e32 v50, v223
	v_pk_mul_f32 v[52:53], v[46:47], v[54:55] op_sel_hi:[1,0]
	v_pk_mul_f32 v[54:55], v[48:49], v[54:55] op_sel_hi:[1,0]
	ds_write2_b32 v51, v52, v53 offset1:1
	ds_write2_b32 v51, v54, v55 offset0:2 offset1:3
	s_cbranch_execnz .LBB0_1608

.LBB0_1608:
	s_waitcnt vmcnt(10)
	v_pk_mul_f32 v[42:43], v[42:43], v[50:51] op_sel_hi:[1,0]
	v_add_u32_e32 v46, v88, v103
	ds_write2_b32 v46, v42, v43 offset1:1
	v_pk_mul_f32 v[42:43], v[44:45], v[50:51] op_sel_hi:[1,0]
	ds_write2_b32 v46, v42, v43 offset0:2 offset1:3
	s_and_b64 vcc, exec, s[0:1]
	v_add_u32_e32 v43, v88, v104
	s_cbranch_vccnz .LBB0_1642
	s_ashr_i32 s15, s14, 31
	v_readlane_b32 s72, v254, 10
	v_lshl_add_u64 v[44:45], s[14:15], 0, v[66:67]
	v_readlane_b32 s82, v254, 20
	v_readlane_b32 s83, v254, 21
	v_readlane_b32 s73, v254, 11
	s_nop 0
	v_lshl_add_u64 v[44:45], v[44:45], 2, s[82:83]
	v_readlane_b32 s74, v254, 12
	v_readlane_b32 s75, v254, 13
	v_readlane_b32 s76, v254, 14
	v_readlane_b32 s77, v254, 15
	v_readlane_b32 s78, v254, 16
	v_readlane_b32 s79, v254, 17
	v_readlane_b32 s80, v254, 18
	v_readlane_b32 s81, v254, 19
	v_readlane_b32 s84, v254, 22
	v_readlane_b32 s85, v254, 23
	v_readlane_b32 s86, v254, 24
	v_readlane_b32 s87, v254, 25
	s_waitcnt vmcnt(8)
	v_mov_b32_e32 v46, v224
	v_mov_b32_e32 v42, v225
	v_pk_mul_f32 v[44:45], v[38:39], v[46:47] op_sel_hi:[1,0]
	v_pk_mul_f32 v[46:47], v[40:41], v[46:47] op_sel_hi:[1,0]
	ds_write2_b32 v43, v44, v45 offset1:1
	ds_write2_b32 v43, v46, v47 offset0:2 offset1:3
	s_cbranch_execnz .LBB0_1611

.LBB0_1611:
	s_waitcnt vmcnt(8)
	v_pk_mul_f32 v[34:35], v[34:35], v[42:43] op_sel_hi:[1,0]
	v_add_u32_e32 v38, v88, v105
	ds_write2_b32 v38, v34, v35 offset1:1
	v_pk_mul_f32 v[34:35], v[36:37], v[42:43] op_sel_hi:[1,0]
	ds_write2_b32 v38, v34, v35 offset0:2 offset1:3
	s_and_b64 vcc, exec, s[0:1]
	v_add_u32_e32 v35, v88, v106
	s_cbranch_vccnz .LBB0_1643
	s_ashr_i32 s15, s14, 31
	v_readlane_b32 s72, v254, 10
	v_lshl_add_u64 v[36:37], s[14:15], 0, v[66:67]
	v_readlane_b32 s82, v254, 20
	v_readlane_b32 s83, v254, 21
	v_readlane_b32 s73, v254, 11
	s_nop 0
	v_lshl_add_u64 v[36:37], v[36:37], 2, s[82:83]
	v_readlane_b32 s74, v254, 12
	v_readlane_b32 s75, v254, 13
	v_readlane_b32 s76, v254, 14
	v_readlane_b32 s77, v254, 15
	v_readlane_b32 s78, v254, 16
	v_readlane_b32 s79, v254, 17
	v_readlane_b32 s80, v254, 18
	v_readlane_b32 s81, v254, 19
	v_readlane_b32 s84, v254, 22
	v_readlane_b32 s85, v254, 23
	v_readlane_b32 s86, v254, 24
	v_readlane_b32 s87, v254, 25
	s_waitcnt vmcnt(6)
	v_mov_b32_e32 v38, v226
	v_mov_b32_e32 v34, v227
	v_pk_mul_f32 v[36:37], v[30:31], v[38:39] op_sel_hi:[1,0]
	v_pk_mul_f32 v[38:39], v[32:33], v[38:39] op_sel_hi:[1,0]
	ds_write2_b32 v35, v36, v37 offset1:1
	ds_write2_b32 v35, v38, v39 offset0:2 offset1:3
	s_cbranch_execnz .LBB0_1614

.LBB0_1614:
	s_waitcnt vmcnt(6)
	v_pk_mul_f32 v[26:27], v[26:27], v[34:35] op_sel_hi:[1,0]
	v_add_u32_e32 v30, v88, v107
	ds_write2_b32 v30, v26, v27 offset1:1
	v_pk_mul_f32 v[26:27], v[28:29], v[34:35] op_sel_hi:[1,0]
	ds_write2_b32 v30, v26, v27 offset0:2 offset1:3
	s_and_b64 vcc, exec, s[0:1]
	v_add_u32_e32 v27, v88, v108
	s_cbranch_vccnz .LBB0_1644
	s_ashr_i32 s15, s14, 31
	v_readlane_b32 s72, v254, 10
	v_lshl_add_u64 v[28:29], s[14:15], 0, v[66:67]
	v_readlane_b32 s82, v254, 20
	v_readlane_b32 s83, v254, 21
	v_readlane_b32 s73, v254, 11
	s_nop 0
	v_lshl_add_u64 v[28:29], v[28:29], 2, s[82:83]
	v_readlane_b32 s74, v254, 12
	v_readlane_b32 s75, v254, 13
	v_readlane_b32 s76, v254, 14
	v_readlane_b32 s77, v254, 15
	v_readlane_b32 s78, v254, 16
	v_readlane_b32 s79, v254, 17
	v_readlane_b32 s80, v254, 18
	v_readlane_b32 s81, v254, 19
	v_readlane_b32 s84, v254, 22
	v_readlane_b32 s85, v254, 23
	v_readlane_b32 s86, v254, 24
	v_readlane_b32 s87, v254, 25
	s_waitcnt vmcnt(4)
	v_mov_b32_e32 v30, v228
	v_mov_b32_e32 v26, v229
	v_pk_mul_f32 v[28:29], v[22:23], v[30:31] op_sel_hi:[1,0]
	v_pk_mul_f32 v[30:31], v[24:25], v[30:31] op_sel_hi:[1,0]
	ds_write2_b32 v27, v28, v29 offset1:1
	ds_write2_b32 v27, v30, v31 offset0:2 offset1:3
	s_cbranch_execnz .LBB0_1617

.LBB0_1617:
	s_waitcnt vmcnt(4)
	v_pk_mul_f32 v[22:23], v[18:19], v[26:27] op_sel_hi:[1,0]
	v_add_u32_e32 v19, v88, v109
	v_pk_mul_f32 v[20:21], v[20:21], v[26:27] op_sel_hi:[1,0]
	ds_write2_b32 v19, v20, v21 offset0:2 offset1:3
	s_and_b64 vcc, exec, s[0:1]
	v_add_u32_e32 v20, 0x410, v19
	v_add_u32_e32 v21, 0x418, v19
	ds_write2_b32 v19, v22, v23 offset1:1
	s_cbranch_vccnz .LBB0_1645
	s_ashr_i32 s15, s14, 31
	v_readlane_b32 s72, v254, 10
	v_lshl_add_u64 v[22:23], s[14:15], 0, v[66:67]
	v_readlane_b32 s82, v254, 20
	v_readlane_b32 s83, v254, 21
	v_readlane_b32 s73, v254, 11
	s_nop 0
	v_lshl_add_u64 v[22:23], v[22:23], 2, s[82:83]
	v_readlane_b32 s74, v254, 12
	v_readlane_b32 s75, v254, 13
	v_readlane_b32 s76, v254, 14
	v_readlane_b32 s77, v254, 15
	v_readlane_b32 s78, v254, 16
	v_readlane_b32 s79, v254, 17
	v_readlane_b32 s80, v254, 18
	v_readlane_b32 s81, v254, 19
	v_readlane_b32 s84, v254, 22
	v_readlane_b32 s85, v254, 23
	v_readlane_b32 s86, v254, 24
	v_readlane_b32 s87, v254, 25
	s_waitcnt vmcnt(2)
	v_mov_b32_e32 v24, v230
	v_mov_b32_e32 v18, v231
	v_pk_mul_f32 v[22:23], v[14:15], v[24:25] op_sel_hi:[1,0]
	v_pk_mul_f32 v[24:25], v[16:17], v[24:25] op_sel_hi:[1,0]
	ds_write2_b32 v20, v22, v23 offset1:1
	ds_write2_b32 v21, v24, v25 offset1:1
	s_cbranch_execnz .LBB0_1620

.LBB0_1620:
	s_waitcnt vmcnt(2)
	v_pk_mul_f32 v[10:11], v[10:11], v[18:19] op_sel_hi:[1,0]
	v_add_u32_e32 v14, 0x820, v19
	ds_write2_b32 v14, v10, v11 offset1:1
	v_pk_mul_f32 v[10:11], v[12:13], v[18:19] op_sel_hi:[1,0]
	v_add_u32_e32 v12, 0x828, v19
	ds_write2_b32 v12, v10, v11 offset1:1
	s_and_b64 vcc, exec, s[0:1]
	v_add_u32_e32 v11, 0xc30, v19
	v_add_u32_e32 v12, 0xc38, v19
	s_cbranch_vccnz .LBB0_1646
	s_ashr_i32 s15, s14, 31
	v_readlane_b32 s72, v254, 10
	v_lshl_add_u64 v[14:15], s[14:15], 0, v[66:67]
	v_readlane_b32 s82, v254, 20
	v_readlane_b32 s83, v254, 21
	v_readlane_b32 s73, v254, 11
	s_nop 0
	v_lshl_add_u64 v[14:15], v[14:15], 2, s[82:83]
	v_readlane_b32 s74, v254, 12
	v_readlane_b32 s75, v254, 13
	v_readlane_b32 s76, v254, 14
	v_readlane_b32 s77, v254, 15
	v_readlane_b32 s78, v254, 16
	v_readlane_b32 s79, v254, 17
	v_readlane_b32 s80, v254, 18
	v_readlane_b32 s81, v254, 19
	v_readlane_b32 s84, v254, 22
	v_readlane_b32 s85, v254, 23
	v_readlane_b32 s86, v254, 24
	v_readlane_b32 s87, v254, 25
	s_waitcnt vmcnt(0)
	v_mov_b32_e32 v16, v232
	v_mov_b32_e32 v10, v233
	v_pk_mul_f32 v[14:15], v[6:7], v[16:17] op_sel_hi:[1,0]
	v_pk_mul_f32 v[16:17], v[8:9], v[16:17] op_sel_hi:[1,0]
	ds_write2_b32 v11, v14, v15 offset1:1
	ds_write2_b32 v12, v16, v17 offset1:1
	s_cbranch_execnz .LBB0_1512
	s_branch .LBB0_1511
